# P9 GEMM: one static s_setprio 1 for the younger wave half (waves 4-7) before the unit loop, per-segment toggles deleted
# speedup vs baseline: 1.0041x; 1.0041x over previous
; #define PG8_STAGE(bufoff, gbase, voff) do { _Pragma("unroll") for (int _i = 0; _i < 2; ++_i) \
;         __builtin_amdgcn_global_load_lds((const unsigned*)((const char*)(gbase) + (voff)[_i]), (LAS unsigned*)(lds + (bufoff) + ldsw + _i * 8192), 16, 0, 0); } while (0)
; #define PG8_WAIT_V(n) asm volatile("s_waitcnt vmcnt(" #n ")" ::: "memory")
; #define PG8_BAR __builtin_amdgcn_s_barrier()
; template <class Epi, class Sched, bool ALIGN_EPI = true, bool SP2 = true>
; __device__ __forceinline__ void gemm_phase(LAS unsigned char* lds, const Gemm g, const Sched& S, const Epi& E) {
;     const int tid = threadIdx.x, wid = __builtin_amdgcn_readfirstlane(tid >> 6), lane = tid & 63, wr = wid >> 2, wc = wid & 3, fr = lane & 15, fq = lane >> 4;
;     const int K = g.K, nt = K / BK;
;     unsigned voffA[2], voffB[2];
; #pragma unroll
;     for (int i = 0; i < 2; ++i) { int R, C; stage_rc(tid * 16 + i * 8192, R, C); const int Rb = Epi::PERM ? ((R & ~31) + perm32(R & 31)) : R;
;         voffA[i] = (unsigned)(R * K + C) * 2u; voffB[i] = (unsigned)(Rb * K + C) * 2u; }
;     const size_t kstep = (size_t)(BK * 2);
;     const size_t hstep = (size_t)HALF * K * 2;
;     const size_t tstep = 2 * hstep;
;     const unsigned ldsw = (unsigned)wid * 1024u;
;     const int aoff = lds_byte(wr * 64 + fr, fq * 8), boff = lds_byte(wc * 32 + fr, fq * 8);
;     ...
;     const char* cA = PG8_ABASE(cur); const char* cB = PG8_BBASE(cur);
;     S.a_ready(cur);
;     if constexpr (SP2) {
;         PG8_STAGE(PG8_SB(0, 0), cB, voffB); PG8_STAGE(PG8_SB(0, 1), cB + hstep, voffB); PG8_STAGE(PG8_SA(0, 0), cA, voffA); PG8_STAGE(PG8_SA(0, 1), cA + hstep, voffA);
;         if (wr == 1) PG8_BAR;
;         PG8_WAIT_V(2); PG8_BAR;
;         PG8_STAGE(PG8_SB(1, 0), cB + kstep, voffB); PG8_STAGE(PG8_SA(1, 0), cA + kstep, voffA); PG8_STAGE(PG8_SB(1, 1), cB + hstep + kstep, voffB);
;         PG8_WAIT_V(6); PG8_BAR;
.LBB0_1804:
	s_add_u32 s16, s10, 0x80000
	s_addc_u32 s17, s11, 0
	s_lshl_b32 s3, s18, 5
	s_mov_b64 s[18:19], 0x80
	s_and_b32 s24, s3, 0x60
	s_add_i32 m0, s40, 0x18000
	v_lshl_add_u64 v[8:9], v[8:9], 0, s[18:19]
	s_lshl_b32 s21, s20, 13
	s_lshl_b32 s25, s24, 7
	s_waitcnt vmcnt(2)
	s_barrier
	global_load_lds_dwordx4 v[8:9], off
	v_lshl_add_u64 v[6:7], v[6:7], 0, s[18:19]
	s_add_i32 m0, s40, 0x1a000
	s_add_i32 s45, s40, 0x8000
	s_add_i32 s46, s40, 0xa000
	global_load_lds_dwordx4 v[6:7], off
	v_lshl_add_u64 v[2:3], v[2:3], 0, s[18:19]
	s_mov_b32 m0, s45
	s_add_u32 s22, s30, 0x100080
	global_load_lds_dwordx4 v[2:3], off
	v_lshl_add_u64 v[2:3], v[4:5], 0, s[18:19]
	s_mov_b32 m0, s46
	s_addc_u32 s23, s31, 0
	global_load_lds_dwordx4 v[2:3], off
	s_add_i32 m0, s40, 0x1c000
	v_lshl_add_u64 v[2:3], s[22:23], 0, v[134:135]
	global_load_lds_dwordx4 v[2:3], off
	v_lshl_add_u64 v[2:3], s[22:23], 0, v[130:131]
	s_add_i32 m0, s40, 0x1e000
	v_and_b32_e32 v4, 32, v1
	global_load_lds_dwordx4 v[2:3], off
	v_and_b32_e32 v3, 15, v0
	v_and_b32_e32 v2, 48, v0
	s_waitcnt vmcnt(0)
	v_lshl_or_b32 v166, s20, 6, v3
	v_lshl_or_b32 v3, v3, 6, v2
	s_sext_i32_i16 s3, s0
	v_bitop3_b32 v5, v3, s21, v4 bitop3:0xde
	v_lshlrev_b32_e32 v3, 6, v0
	s_movk_i32 s0, 0x3c0
	s_cmpk_lt_u32 s1, 0x100
	v_and_or_b32 v3, v3, s0, v2
	s_cselect_b64 s[20:21], -1, 0
	s_lshl_b32 s0, s24, 1
	s_add_u32 s0, s10, s0
	v_bitop3_b32 v167, s25, v3, v4 bitop3:0xf6
	s_addc_u32 s1, s11, 0
	v_mov_b32_e32 v3, v135
	v_lshl_add_u64 v[2:3], s[0:1], 0, v[2:3]
	s_mov_b64 s[0:1], 0x8a00000
	v_lshl_add_u64 v[138:139], v[2:3], 0, s[0:1]
	v_lshlrev_b32_e32 v2, 10, v0
	s_waitcnt vmcnt(6)
	s_barrier
	s_load_dword s0, s[56:57], 0xe0
	v_and_b32_e32 v2, 0x60000, v2
	v_lshlrev_b32_e32 v3, 13, v13
	v_or3_b32 v2, v11, v2, v3
	v_add_u32_e32 v140, v2, v12
	v_lshlrev_b32_e32 v2, 6, v10
	v_and_b32_e32 v2, 0xe0000, v2
	v_or3_b32 v2, v11, v2, v3
	s_add_i32 s48, 0, 0x10000
	s_add_i32 s49, 0, 0x14000
	s_waitcnt lgkmcnt(0)
	s_ashr_i32 s47, s0, 31
	v_mov_b32_e32 v141, v135
	v_add_u32_e32 v142, v2, v12
	v_mov_b32_e32 v143, v135
	v_mov_b64_e32 v[144:145], 0x1580
	v_mov_b64_e32 v[146:147], 0x157f
	v_add_u32_e32 v168, s48, v167
	v_add_u32_e32 v169, s49, v167
	v_add_u32_e32 v170, 0, v5
	v_mov_b32_e32 v171, 0x358637bd
	s_mov_b32 s50, 0xf800000
	v_mov_b32_e32 v172, 0x260
	s_movk_i32 s51, 0x5600
	s_and_b64 vcc, exec, s[20:21]
	s_cbranch_vccnz .Lsp1810
	s_setprio 1
.Lsp1810:
	s_branch .LBB0_1807
.LBB0_1805:
	s_mov_b64 s[0:1], 0

; #define PG8_WAIT_V(n) asm volatile("s_waitcnt vmcnt(" #n ")" ::: "memory")
; #define PG8_BAR __builtin_amdgcn_s_barrier()
; template <class Epi, class Sched, bool ALIGN_EPI = true, bool SP2 = true>
; __device__ __forceinline__ void gemm_phase(LAS unsigned char* lds, const Gemm g, const Sched& S, const Epi& E) {
;     ...
;     PG8_WAIT_V(0);
;     if constexpr (!ALIGN_EPI) { if (wr == 0) PG8_BAR; }
;     PG8_BAR;
.LBB0_1816:
	s_setprio 0
	s_waitcnt vmcnt(0)
	s_barrier
